# added: grid-barrier XCD-leader releases its XCD (XGEN add) before its own L1 invalidate
# baseline (speedup 1.0000x reference)
; __device__ __forceinline__ unsigned xb_ld(unsigned* p)              { return __hip_atomic_load(p, __ATOMIC_RELAXED, __HIP_MEMORY_SCOPE_AGENT); }
; __device__ __forceinline__ unsigned xb_add(unsigned* p, unsigned v) { return __hip_atomic_fetch_add(p, v, __ATOMIC_RELAXED, __HIP_MEMORY_SCOPE_AGENT); }
; #define XB_SPIN(cond, bar) do { unsigned _sp = 0; while (cond) { __builtin_amdgcn_s_sleep(1); \
;     if ((++_sp & 255u) == 0u) { if (xb_ld(&(bar)[XB_TMO])) break; if (_sp > XB_SPIN_CAP) { atomicAdd(&(bar)[XB_TMO], 1u); break; } } } } while (0)
; __device__ __forceinline__ void xcd_barrier(const XcdBarrier& b) {
;     ...
;     if (old + 1u == (gen + 1u) * nloc) {
;       __builtin_amdgcn_fence(__ATOMIC_RELEASE, "agent");
;       asm volatile("s_waitcnt vmcnt(0)" ::: "memory");
;       const unsigned og = xb_add(&bar[XB_TOP], 1u);
;       const unsigned tg = og / nx;
;       if (og + 1u == (tg + 1u) * nx) xb_add(&bar[XB_TOPGEN], 1u);
;       else XB_SPIN(xb_ld(&bar[XB_TOPGEN]) == tg, bar);
;       __builtin_amdgcn_fence(__ATOMIC_ACQUIRE, "agent");
;       xb_add(&bar[XB_XGEN(b.x)], 1u);
;       asm volatile("s_waitcnt vmcnt(0)" ::: "memory");
.LBB0_1306:
	s_or_b64 exec, exec, s[2:3]
	s_mov_b64 s[2:3], exec
	v_mbcnt_lo_u32_b32 v0, s2, 0
	v_mbcnt_hi_u32_b32 v0, s3, v0
	v_cmp_eq_u32_e32 vcc, 0, v0
	s_waitcnt vmcnt(0)
	s_and_saveexec_b64 s[20:21], vcc
	s_cbranch_execz .Lxb_inv
	s_bcnt1_i32_b64 s2, s[2:3]
	v_mov_b32_e32 v0, s2
	v_readlane_b32 s2, v254, 7
	v_readlane_b32 s3, v254, 8
	s_nop 4
	global_atomic_add v133, v0, s[2:3]
.Lxb_inv:
	buffer_inv sc1
	s_branch .LBB0_221
